# nt hint: input-projection epilogue stores + f32 weight loads of the in-launch weight conversions
# speedup vs baseline: 1.0100x; 1.0088x over previous
.LBB0_598:
	s_ashr_i32 s5, s4, 7
	s_lshl_b32 s4, s5, 6
	s_lshl_b32 s5, s5, 12
	s_sub_i32 s12, s10, s5
	v_add_u32_e32 v2, s12, v1
	s_waitcnt lgkmcnt(0)
	v_lshl_add_u64 v[6:7], v[2:3], 2, s[64:65]
	v_mov_b32_e32 v2, 0
	s_andn2_b64 vcc, exec, s[8:9]
	v_mov_b32_e32 v47, 0
	s_cbranch_vccnz .LBB0_624
	v_or_b32_e32 v48, s4, v8
	v_ashrrev_i32_e32 v49, 31, v48
	v_or_b32_e32 v50, s4, v9
	v_or_b32_e32 v52, s4, v10
	v_or_b32_e32 v54, s4, v11
	v_lshlrev_b64 v[48:49], 14, v[48:49]
	v_ashrrev_i32_e32 v51, 31, v50
	v_ashrrev_i32_e32 v53, 31, v52
	v_ashrrev_i32_e32 v55, 31, v54
	v_lshl_add_u64 v[48:49], v[6:7], 0, v[48:49]
	v_lshlrev_b64 v[50:51], 14, v[50:51]
	v_lshlrev_b64 v[52:53], 14, v[52:53]
	v_lshlrev_b64 v[54:55], 14, v[54:55]
	v_lshl_add_u64 v[50:51], v[6:7], 0, v[50:51]
	v_lshl_add_u64 v[52:53], v[6:7], 0, v[52:53]
	v_lshl_add_u64 v[54:55], v[6:7], 0, v[54:55]
	global_load_dword v56, v[48:49], off nt
	global_load_dword v57, v[50:51], off nt
	global_load_dword v2, v[52:53], off nt
	global_load_dword v47, v[54:55], off nt
	s_waitcnt vmcnt(2)
	ds_write2_b32 v42, v56, v57 offset1:66
	s_mov_b64 s[8:9], -1
	s_and_b64 vcc, exec, s[6:7]
	s_waitcnt vmcnt(0)
	ds_write2_b32 v43, v2, v47 offset1:66
	s_cbranch_vccnz .LBB0_625

.LBB0_601:
	v_or_b32_e32 v48, s4, v12
	v_ashrrev_i32_e32 v49, 31, v48
	v_or_b32_e32 v50, s4, v13
	v_or_b32_e32 v52, s4, v14
	v_or_b32_e32 v54, s4, v15
	v_lshlrev_b64 v[48:49], 14, v[48:49]
	v_ashrrev_i32_e32 v51, 31, v50
	v_ashrrev_i32_e32 v53, 31, v52
	v_ashrrev_i32_e32 v55, 31, v54
	v_lshl_add_u64 v[48:49], v[6:7], 0, v[48:49]
	v_lshlrev_b64 v[50:51], 14, v[50:51]
	v_lshlrev_b64 v[52:53], 14, v[52:53]
	v_lshlrev_b64 v[54:55], 14, v[54:55]
	v_lshl_add_u64 v[50:51], v[6:7], 0, v[50:51]
	v_lshl_add_u64 v[52:53], v[6:7], 0, v[52:53]
	v_lshl_add_u64 v[54:55], v[6:7], 0, v[54:55]
	global_load_dword v56, v[48:49], off nt
	global_load_dword v57, v[50:51], off nt
	global_load_dword v2, v[52:53], off nt
	global_load_dword v47, v[54:55], off nt
	s_waitcnt vmcnt(2)
	ds_write2_b32 v44, v56, v57 offset1:66
	s_mov_b64 s[8:9], -1
	s_and_b64 vcc, exec, s[6:7]
	s_waitcnt vmcnt(0)
	ds_write2_b32 v45, v2, v47 offset1:66
	s_cbranch_vccnz .LBB0_627

.LBB0_603:
	v_or_b32_e32 v48, s4, v16
	v_ashrrev_i32_e32 v49, 31, v48
	v_or_b32_e32 v50, s4, v17
	v_or_b32_e32 v52, s4, v18
	v_or_b32_e32 v54, s4, v19
	v_lshlrev_b64 v[48:49], 14, v[48:49]
	v_ashrrev_i32_e32 v51, 31, v50
	v_ashrrev_i32_e32 v53, 31, v52
	v_ashrrev_i32_e32 v55, 31, v54
	v_lshl_add_u64 v[48:49], v[6:7], 0, v[48:49]
	v_lshlrev_b64 v[50:51], 14, v[50:51]
	v_lshlrev_b64 v[52:53], 14, v[52:53]
	v_lshlrev_b64 v[54:55], 14, v[54:55]
	v_lshl_add_u64 v[50:51], v[6:7], 0, v[50:51]
	v_lshl_add_u64 v[52:53], v[6:7], 0, v[52:53]
	v_lshl_add_u64 v[54:55], v[6:7], 0, v[54:55]
	global_load_dword v56, v[48:49], off nt
	global_load_dword v57, v[50:51], off nt
	global_load_dword v2, v[52:53], off nt
	global_load_dword v47, v[54:55], off nt
	s_waitcnt vmcnt(2)
	ds_write2_b32 v46, v56, v57 offset1:66

.LBB0_606:
	v_mov_b32_e32 v47, 0
	s_andn2_b64 vcc, exec, s[8:9]
	v_mov_b32_e32 v48, 0
	s_cbranch_vccnz .LBB0_608
	v_or_b32_e32 v48, s4, v20
	v_ashrrev_i32_e32 v49, 31, v48
	v_lshlrev_b64 v[48:49], 14, v[48:49]
	v_lshl_add_u64 v[50:51], v[6:7], 0, v[48:49]
	v_or_b32_e32 v48, s4, v21
	v_ashrrev_i32_e32 v49, 31, v48
	v_lshlrev_b64 v[48:49], 14, v[48:49]
	v_lshl_add_u64 v[52:53], v[6:7], 0, v[48:49]
	v_or_b32_e32 v48, s4, v22
	v_ashrrev_i32_e32 v49, 31, v48
	v_lshlrev_b64 v[48:49], 14, v[48:49]
	v_lshl_add_u64 v[54:55], v[6:7], 0, v[48:49]
	v_or_b32_e32 v48, s4, v23
	v_ashrrev_i32_e32 v49, 31, v48
	v_lshlrev_b64 v[48:49], 14, v[48:49]
	v_lshl_add_u64 v[56:57], v[6:7], 0, v[48:49]
	global_load_dword v49, v[50:51], off nt
	global_load_dword v58, v[52:53], off nt
	global_load_dword v47, v[54:55], off nt
	global_load_dword v48, v[56:57], off nt
	s_waitcnt vmcnt(2)
	ds_write2_b32 v2, v49, v58 offset0:8 offset1:74

.LBB0_610:
	v_mov_b32_e32 v47, 0
	s_andn2_b64 vcc, exec, s[8:9]
	v_mov_b32_e32 v48, 0
	s_cbranch_vccnz .LBB0_612
	v_or_b32_e32 v48, s4, v24
	v_ashrrev_i32_e32 v49, 31, v48
	v_lshlrev_b64 v[48:49], 14, v[48:49]
	v_lshl_add_u64 v[50:51], v[6:7], 0, v[48:49]
	v_or_b32_e32 v48, s4, v25
	v_ashrrev_i32_e32 v49, 31, v48
	v_lshlrev_b64 v[48:49], 14, v[48:49]
	v_lshl_add_u64 v[52:53], v[6:7], 0, v[48:49]
	v_or_b32_e32 v48, s4, v26
	v_ashrrev_i32_e32 v49, 31, v48
	v_lshlrev_b64 v[48:49], 14, v[48:49]
	v_lshl_add_u64 v[54:55], v[6:7], 0, v[48:49]
	v_or_b32_e32 v48, s4, v27
	v_ashrrev_i32_e32 v49, 31, v48
	v_lshlrev_b64 v[48:49], 14, v[48:49]
	v_lshl_add_u64 v[56:57], v[6:7], 0, v[48:49]
	global_load_dword v49, v[50:51], off nt
	global_load_dword v58, v[52:53], off nt
	global_load_dword v47, v[54:55], off nt
	global_load_dword v48, v[56:57], off nt
	s_waitcnt vmcnt(2)
	ds_write2_b32 v2, v49, v58 offset0:16 offset1:82

.LBB0_614:
	v_mov_b32_e32 v47, 0
	s_andn2_b64 vcc, exec, s[8:9]
	v_mov_b32_e32 v48, 0
	s_cbranch_vccnz .LBB0_616
	v_or_b32_e32 v48, s4, v28
	v_ashrrev_i32_e32 v49, 31, v48
	v_lshlrev_b64 v[48:49], 14, v[48:49]
	v_lshl_add_u64 v[50:51], v[6:7], 0, v[48:49]
	v_or_b32_e32 v48, s4, v29
	v_ashrrev_i32_e32 v49, 31, v48
	v_lshlrev_b64 v[48:49], 14, v[48:49]
	v_lshl_add_u64 v[52:53], v[6:7], 0, v[48:49]
	v_or_b32_e32 v48, s4, v30
	v_ashrrev_i32_e32 v49, 31, v48
	v_lshlrev_b64 v[48:49], 14, v[48:49]
	v_lshl_add_u64 v[54:55], v[6:7], 0, v[48:49]
	v_or_b32_e32 v48, s4, v31
	v_ashrrev_i32_e32 v49, 31, v48
	v_lshlrev_b64 v[48:49], 14, v[48:49]
	v_lshl_add_u64 v[56:57], v[6:7], 0, v[48:49]
	global_load_dword v49, v[50:51], off nt
	global_load_dword v58, v[52:53], off nt
	global_load_dword v47, v[54:55], off nt
	global_load_dword v48, v[56:57], off nt
	s_waitcnt vmcnt(2)
	ds_write2_b32 v2, v49, v58 offset0:24 offset1:90

.LBB0_618:
	v_mov_b32_e32 v47, 0
	s_andn2_b64 vcc, exec, s[8:9]
	v_mov_b32_e32 v48, 0
	s_cbranch_vccnz .LBB0_620
	v_or_b32_e32 v48, s4, v32
	v_ashrrev_i32_e32 v49, 31, v48
	v_lshlrev_b64 v[48:49], 14, v[48:49]
	v_lshl_add_u64 v[50:51], v[6:7], 0, v[48:49]
	v_or_b32_e32 v48, s4, v33
	v_ashrrev_i32_e32 v49, 31, v48
	v_lshlrev_b64 v[48:49], 14, v[48:49]
	v_lshl_add_u64 v[52:53], v[6:7], 0, v[48:49]
	v_or_b32_e32 v48, s4, v34
	v_ashrrev_i32_e32 v49, 31, v48
	v_lshlrev_b64 v[48:49], 14, v[48:49]
	v_lshl_add_u64 v[54:55], v[6:7], 0, v[48:49]
	v_or_b32_e32 v48, s4, v35
	v_ashrrev_i32_e32 v49, 31, v48
	v_lshlrev_b64 v[48:49], 14, v[48:49]
	v_lshl_add_u64 v[56:57], v[6:7], 0, v[48:49]
	global_load_dword v49, v[50:51], off nt
	global_load_dword v58, v[52:53], off nt
	global_load_dword v47, v[54:55], off nt
	global_load_dword v48, v[56:57], off nt
	s_waitcnt vmcnt(2)
	ds_write2_b32 v2, v49, v58 offset0:32 offset1:98

.LBB0_622:
	v_mov_b32_e32 v47, 0
	s_andn2_b64 vcc, exec, s[8:9]
	v_mov_b32_e32 v48, 0
	s_cbranch_vccnz .LBB0_595
	v_or_b32_e32 v48, s4, v36
	v_ashrrev_i32_e32 v49, 31, v48
	v_lshlrev_b64 v[48:49], 14, v[48:49]
	v_lshl_add_u64 v[50:51], v[6:7], 0, v[48:49]
	v_or_b32_e32 v48, s4, v37
	v_ashrrev_i32_e32 v49, 31, v48
	v_lshlrev_b64 v[48:49], 14, v[48:49]
	v_lshl_add_u64 v[52:53], v[6:7], 0, v[48:49]
	v_or_b32_e32 v48, s4, v38
	v_ashrrev_i32_e32 v49, 31, v48
	v_lshlrev_b64 v[48:49], 14, v[48:49]
	v_lshl_add_u64 v[54:55], v[6:7], 0, v[48:49]
	v_or_b32_e32 v48, s4, v39
	v_ashrrev_i32_e32 v49, 31, v48
	v_lshlrev_b64 v[48:49], 14, v[48:49]
	v_lshl_add_u64 v[6:7], v[6:7], 0, v[48:49]
	global_load_dword v49, v[50:51], off nt
	global_load_dword v56, v[52:53], off nt
	global_load_dword v47, v[54:55], off nt
	global_load_dword v48, v[6:7], off nt
	s_waitcnt vmcnt(2)
	ds_write2_b32 v2, v49, v56 offset0:40 offset1:106
	s_branch .LBB0_595

.LBB0_968:
	s_or_b64 exec, exec, s[0:1]
	s_mul_i32 s0, s17, 0xfffffe98
	s_add_i32 s0, s10, s0
	s_cmp_lt_i32 s0, 48
	s_cselect_b64 s[0:1], -1, 0
	v_cmp_gt_i32_e32 vcc, 0, v2
	s_and_saveexec_b64 s[6:7], vcc
	s_xor_b64 s[6:7], exec, s[6:7]
	ds_write2_b32 v43, v3, v3 offset1:66
	s_or_saveexec_b64 s[8:9], s[6:7]
	s_lshl_b32 s6, s17, 6
	v_cndmask_b32_e64 v51, 1.0, v42, s[0:1]
	s_waitcnt lgkmcnt(0)
	v_lshl_add_u64 v[6:7], v[2:3], 2, s[66:67]
	v_mov_b32_e32 v2, 0
	v_mov_b32_e32 v52, 0
	s_xor_b64 exec, exec, s[8:9]
	s_cbranch_execz .LBB0_972
	v_or_b32_e32 v2, s6, v8
	v_mad_i64_i32 v[52:53], s[0:1], v2, s15, v[6:7]
	v_or_b32_e32 v2, s6, v9
	v_mad_i64_i32 v[54:55], s[0:1], v2, s15, v[6:7]
	global_load_dword v2, v[52:53], off nt
	global_load_dword v56, v[54:55], off nt
	v_or_b32_e32 v52, s6, v10
	v_mad_i64_i32 v[52:53], s[0:1], v52, s15, v[6:7]
	v_or_b32_e32 v54, s6, v11
	v_mad_i64_i32 v[54:55], s[0:1], v54, s15, v[6:7]
	global_load_dword v53, v[52:53], off nt
	s_nop 0
	global_load_dword v52, v[54:55], off nt
	s_waitcnt vmcnt(3)
	v_mul_f32_e32 v2, v51, v2
	s_waitcnt vmcnt(2)
	v_mul_f32_e32 v54, v51, v56
	ds_write2_b32 v43, v2, v54 offset1:66
	s_waitcnt vmcnt(1)
	v_mul_f32_e32 v2, v51, v53
.LBB0_972:
	s_or_b64 exec, exec, s[8:9]
	s_waitcnt vmcnt(0)
	v_mul_f32_e32 v52, v51, v52
	ds_write2_b32 v44, v2, v52 offset1:66
	s_and_saveexec_b64 s[0:1], vcc
	s_xor_b64 s[0:1], exec, s[0:1]
	ds_write2_b32 v45, v3, v3 offset1:66
	s_or_saveexec_b64 s[0:1], s[0:1]
	v_mov_b32_e32 v2, 0
	v_mov_b32_e32 v52, 0
	s_xor_b64 exec, exec, s[0:1]
	s_cbranch_execz .LBB0_976
	v_or_b32_e32 v2, s6, v12
	v_mad_i64_i32 v[52:53], s[8:9], v2, s15, v[6:7]
	v_or_b32_e32 v2, s6, v13
	v_mad_i64_i32 v[54:55], s[8:9], v2, s15, v[6:7]
	global_load_dword v2, v[52:53], off nt
	global_load_dword v56, v[54:55], off nt
	v_or_b32_e32 v52, s6, v14
	v_mad_i64_i32 v[52:53], s[8:9], v52, s15, v[6:7]
	v_or_b32_e32 v54, s6, v15
	v_mad_i64_i32 v[54:55], s[8:9], v54, s15, v[6:7]
	global_load_dword v53, v[52:53], off nt
	s_nop 0
	global_load_dword v52, v[54:55], off nt
	s_waitcnt vmcnt(3)
	v_mul_f32_e32 v2, v51, v2
	s_waitcnt vmcnt(2)
	v_mul_f32_e32 v54, v51, v56
	ds_write2_b32 v45, v2, v54 offset1:66
	s_waitcnt vmcnt(1)
	v_mul_f32_e32 v2, v51, v53
.LBB0_976:
	s_or_b64 exec, exec, s[0:1]
	s_waitcnt vmcnt(0)
	v_mul_f32_e32 v52, v51, v52
	ds_write2_b32 v46, v2, v52 offset1:66
	s_and_saveexec_b64 s[0:1], vcc
	s_xor_b64 s[0:1], exec, s[0:1]
	ds_write2_b32 v47, v3, v3 offset1:66
	s_or_saveexec_b64 s[0:1], s[0:1]
	v_mov_b32_e32 v2, 0
	v_mov_b32_e32 v52, 0
	s_xor_b64 exec, exec, s[0:1]
	s_cbranch_execz .LBB0_980
	v_or_b32_e32 v2, s6, v16
	v_mad_i64_i32 v[52:53], s[8:9], v2, s15, v[6:7]
	v_or_b32_e32 v2, s6, v17
	v_mad_i64_i32 v[54:55], s[8:9], v2, s15, v[6:7]
	global_load_dword v2, v[52:53], off nt
	global_load_dword v56, v[54:55], off nt
	v_or_b32_e32 v52, s6, v18
	v_mad_i64_i32 v[52:53], s[8:9], v52, s15, v[6:7]
	v_or_b32_e32 v54, s6, v19
	v_mad_i64_i32 v[54:55], s[8:9], v54, s15, v[6:7]
	global_load_dword v53, v[52:53], off nt
	s_nop 0
	global_load_dword v52, v[54:55], off nt
	s_waitcnt vmcnt(3)
	v_mul_f32_e32 v2, v51, v2
	s_waitcnt vmcnt(2)
	v_mul_f32_e32 v54, v51, v56
	ds_write2_b32 v47, v2, v54 offset1:66
	s_waitcnt vmcnt(1)
	v_mul_f32_e32 v2, v51, v53
.LBB0_980:
	s_or_b64 exec, exec, s[0:1]
	s_waitcnt vmcnt(0)
	v_mul_f32_e32 v52, v51, v52
	ds_write2_b32 v47, v2, v52 offset0:132 offset1:198
	s_and_saveexec_b64 s[0:1], vcc
	s_xor_b64 s[0:1], exec, s[0:1]
	ds_write2_b32 v48, v3, v3 offset0:8 offset1:74
	s_or_saveexec_b64 s[0:1], s[0:1]
	v_mov_b32_e32 v2, 0
	v_mov_b32_e32 v52, 0
	s_xor_b64 exec, exec, s[0:1]
	s_cbranch_execz .LBB0_984
	v_or_b32_e32 v2, s6, v20
	v_mad_i64_i32 v[52:53], s[8:9], v2, s15, v[6:7]
	v_or_b32_e32 v2, s6, v21
	v_mad_i64_i32 v[54:55], s[8:9], v2, s15, v[6:7]
	global_load_dword v2, v[52:53], off nt
	global_load_dword v56, v[54:55], off nt
	v_or_b32_e32 v52, s6, v22
	v_mad_i64_i32 v[52:53], s[8:9], v52, s15, v[6:7]
	v_or_b32_e32 v54, s6, v23
	v_mad_i64_i32 v[54:55], s[8:9], v54, s15, v[6:7]
	global_load_dword v53, v[52:53], off nt
	s_nop 0
	global_load_dword v52, v[54:55], off nt
	s_waitcnt vmcnt(3)
	v_mul_f32_e32 v2, v51, v2
	s_waitcnt vmcnt(2)
	v_mul_f32_e32 v54, v51, v56
	ds_write2_b32 v48, v2, v54 offset0:8 offset1:74
	s_waitcnt vmcnt(1)
	v_mul_f32_e32 v2, v51, v53
.LBB0_984:
	s_or_b64 exec, exec, s[0:1]
	s_waitcnt vmcnt(0)
	v_mul_f32_e32 v52, v51, v52
	ds_write2_b32 v48, v2, v52 offset0:140 offset1:206
	s_and_saveexec_b64 s[0:1], vcc
	s_xor_b64 s[0:1], exec, s[0:1]
	ds_write2_b32 v49, v3, v3 offset0:16 offset1:82
	s_or_saveexec_b64 s[0:1], s[0:1]
	v_mov_b32_e32 v2, 0
	v_mov_b32_e32 v52, 0
	s_xor_b64 exec, exec, s[0:1]
	s_cbranch_execz .LBB0_988
	v_or_b32_e32 v2, s6, v24
	v_mad_i64_i32 v[52:53], s[8:9], v2, s15, v[6:7]
	v_or_b32_e32 v2, s6, v25
	v_mad_i64_i32 v[54:55], s[8:9], v2, s15, v[6:7]
	global_load_dword v2, v[52:53], off nt
	global_load_dword v56, v[54:55], off nt
	v_or_b32_e32 v52, s6, v26
	v_mad_i64_i32 v[52:53], s[8:9], v52, s15, v[6:7]
	v_or_b32_e32 v54, s6, v27
	v_mad_i64_i32 v[54:55], s[8:9], v54, s15, v[6:7]
	global_load_dword v53, v[52:53], off nt
	s_nop 0
	global_load_dword v52, v[54:55], off nt
	s_waitcnt vmcnt(3)
	v_mul_f32_e32 v2, v51, v2
	s_waitcnt vmcnt(2)
	v_mul_f32_e32 v54, v51, v56
	ds_write2_b32 v49, v2, v54 offset0:16 offset1:82
	s_waitcnt vmcnt(1)
	v_mul_f32_e32 v2, v51, v53
.LBB0_988:
	s_or_b64 exec, exec, s[0:1]
	s_waitcnt vmcnt(0)
	v_mul_f32_e32 v52, v51, v52
	ds_write2_b32 v49, v2, v52 offset0:148 offset1:214
	s_and_saveexec_b64 s[0:1], vcc
	s_xor_b64 s[0:1], exec, s[0:1]
	ds_write2_b32 v50, v3, v3 offset0:24 offset1:90
	s_or_saveexec_b64 s[0:1], s[0:1]
	v_mov_b32_e32 v2, 0
	v_mov_b32_e32 v52, 0
	s_xor_b64 exec, exec, s[0:1]
	s_cbranch_execz .LBB0_992
	v_or_b32_e32 v2, s6, v28
	v_mad_i64_i32 v[52:53], s[8:9], v2, s15, v[6:7]
	v_or_b32_e32 v2, s6, v29
	v_mad_i64_i32 v[54:55], s[8:9], v2, s15, v[6:7]
	global_load_dword v2, v[52:53], off nt
	global_load_dword v56, v[54:55], off nt
	v_or_b32_e32 v52, s6, v30
	v_mad_i64_i32 v[52:53], s[8:9], v52, s15, v[6:7]
	v_or_b32_e32 v54, s6, v31
	v_mad_i64_i32 v[54:55], s[8:9], v54, s15, v[6:7]
	global_load_dword v53, v[52:53], off nt
	s_nop 0
	global_load_dword v52, v[54:55], off nt
	s_waitcnt vmcnt(3)
	v_mul_f32_e32 v2, v51, v2
	s_waitcnt vmcnt(2)
	v_mul_f32_e32 v54, v51, v56
	ds_write2_b32 v50, v2, v54 offset0:24 offset1:90
	s_waitcnt vmcnt(1)
	v_mul_f32_e32 v2, v51, v53
.LBB0_992:
	s_or_b64 exec, exec, s[0:1]
	s_waitcnt vmcnt(0)
	v_mul_f32_e32 v52, v51, v52
	ds_write2_b32 v50, v2, v52 offset0:156 offset1:222
	v_add_u32_e32 v2, 0x1000, v47
	s_and_saveexec_b64 s[0:1], vcc
	s_xor_b64 s[0:1], exec, s[0:1]
	ds_write2_b32 v2, v3, v3 offset0:32 offset1:98
	s_or_saveexec_b64 s[0:1], s[0:1]
	v_mov_b32_e32 v52, 0
	v_mov_b32_e32 v53, 0
	s_xor_b64 exec, exec, s[0:1]
	s_cbranch_execz .LBB0_996
	v_or_b32_e32 v52, s6, v32
	v_mad_i64_i32 v[52:53], s[8:9], v52, s15, v[6:7]
	v_or_b32_e32 v54, s6, v33
	v_mad_i64_i32 v[54:55], s[8:9], v54, s15, v[6:7]
	global_load_dword v56, v[52:53], off nt
	global_load_dword v57, v[54:55], off nt
	v_or_b32_e32 v52, s6, v34
	v_mad_i64_i32 v[52:53], s[8:9], v52, s15, v[6:7]
	v_or_b32_e32 v54, s6, v35
	v_mad_i64_i32 v[54:55], s[8:9], v54, s15, v[6:7]
	global_load_dword v52, v[52:53], off nt
	s_nop 0
	global_load_dword v53, v[54:55], off nt
	s_waitcnt vmcnt(3)
	v_mul_f32_e32 v54, v51, v56
	s_waitcnt vmcnt(2)
	v_mul_f32_e32 v55, v51, v57
	ds_write2_b32 v2, v54, v55 offset0:32 offset1:98
	s_waitcnt vmcnt(1)
	v_mul_f32_e32 v52, v51, v52
.LBB0_996:
	s_or_b64 exec, exec, s[0:1]
	s_waitcnt vmcnt(0)
	v_mul_f32_e32 v53, v51, v53
	ds_write2_b32 v2, v52, v53 offset0:164 offset1:230
	v_add_u32_e32 v2, 0x1400, v47
	s_and_saveexec_b64 s[0:1], vcc
	s_xor_b64 s[0:1], exec, s[0:1]
	ds_write2_b32 v2, v3, v3 offset0:40 offset1:106
	s_or_saveexec_b64 s[0:1], s[0:1]
	v_mov_b32_e32 v52, 0
	v_mov_b32_e32 v53, 0
	s_xor_b64 exec, exec, s[0:1]
	s_cbranch_execz .LBB0_957
	v_or_b32_e32 v52, s6, v36
	v_or_b32_e32 v54, s6, v37
	v_mad_i64_i32 v[52:53], s[8:9], v52, s15, v[6:7]
	v_mad_i64_i32 v[54:55], s[8:9], v54, s15, v[6:7]
	global_load_dword v56, v[52:53], off nt
	s_nop 0
	global_load_dword v54, v[54:55], off nt
	v_or_b32_e32 v52, s6, v38
	v_mad_i64_i32 v[52:53], s[8:9], v52, s15, v[6:7]
	v_or_b32_e32 v55, s6, v39
	v_mad_i64_i32 v[6:7], s[8:9], v55, s15, v[6:7]
	global_load_dword v52, v[52:53], off nt
	s_nop 0
	global_load_dword v53, v[6:7], off nt
	s_waitcnt vmcnt(3)
	v_mul_f32_e32 v6, v51, v56
	s_waitcnt vmcnt(2)
	v_mul_f32_e32 v7, v51, v54
	ds_write2_b32 v2, v6, v7 offset0:40 offset1:106
	s_waitcnt vmcnt(1)
	v_mul_f32_e32 v52, v51, v52
	s_branch .LBB0_957
